# S5 inter-chunk scan: second-group loads issued before the 32 zero-padding stores (counted waits +32)
# baseline (speedup 1.0000x reference)
.LBB0_1204:
	s_mov_b64 s[2:3], 0x2000
	v_lshl_add_u64 v[10:11], v[6:7], 0, v[4:5]
	v_lshl_add_u64 v[12:13], v[6:7], 0, v[0:1]
	v_lshl_add_u64 v[6:7], v[6:7], 0, s[2:3]
	s_mov_b32 s2, 0x10701000
	v_add_co_u32_e64 v20, s[2:3], s2, v10
	v_cvt_pk_bf16_f32 v26, v14, s0
	s_nop 0
	v_addc_co_u32_e64 v21, s[2:3], 0, v11, s[2:3]
	v_add_co_u32_e64 v22, s[2:3], s75, v12
	v_cvt_pk_bf16_f32 v27, v15, s0
	s_nop 0
	v_addc_co_u32_e64 v23, s[2:3], 0, v13, s[2:3]
	s_mov_b32 s2, 0xd701000
	s_nop 0
	v_add_co_u32_e64 v12, s[2:3], s2, v12
	v_pk_mul_f32 v[16:17], v[2:3], v[14:15]
	v_pk_mul_f32 v[14:15], v[8:9], v[14:15]
	v_add_co_u32_e32 v18, vcc, 0x10700000, v10
	v_addc_co_u32_e64 v13, s[2:3], 0, v13, s[2:3]
	v_sub_f32_e32 v32, v16, v17
	v_add_f32_e32 v33, v14, v15
	v_addc_co_u32_e32 v19, vcc, 0, v11, vcc
	global_load_dword v36, v[20:21], off
	global_load_dword v37, v[20:21], off offset:256
	global_load_dword v10, v[20:21], off offset:512
	global_load_dword v11, v[20:21], off offset:768
	global_load_dword v38, v[20:21], off offset:1024
	global_load_dword v39, v[20:21], off offset:1280
	global_load_dword v14, v[20:21], off offset:1536
	global_load_dword v15, v[20:21], off offset:1792
	global_load_dword v40, v[20:21], off offset:2048
	global_load_dword v41, v[20:21], off offset:2304
	global_load_dword v16, v[20:21], off offset:2560
	global_load_dword v17, v[20:21], off offset:2816
	global_load_dword v42, v[20:21], off offset:3072
	global_load_dword v43, v[20:21], off offset:3328
	global_load_dword v24, v[20:21], off offset:3584
	global_load_dword v25, v[20:21], off offset:3840
	s_nop 0
	global_store_short v[12:13], v26, off offset:-4096
	global_store_short v[22:23], v27, off offset:128
	global_load_dword v34, v[18:19], off
	global_load_dword v35, v[18:19], off offset:256
	global_load_dword v20, v[18:19], off offset:512
	global_load_dword v21, v[18:19], off offset:768
	global_load_dword v44, v[18:19], off offset:1024
	global_load_dword v45, v[18:19], off offset:1280
	global_load_dword v26, v[18:19], off offset:1536
	global_load_dword v27, v[18:19], off offset:1792
	global_load_dword v46, v[18:19], off offset:2048
	global_load_dword v47, v[18:19], off offset:2304
	global_load_dword v28, v[18:19], off offset:2560
	global_load_dword v29, v[18:19], off offset:2816
	global_load_dword v48, v[18:19], off offset:3072
	global_load_dword v49, v[18:19], off offset:3328
	global_load_dword v30, v[18:19], off offset:3584
	global_load_dword v31, v[18:19], off offset:3840
	global_store_short v[22:23], v1, off offset:256
	global_store_short v[22:23], v1, off offset:384
	global_store_short v[22:23], v1, off offset:768
	global_store_short v[22:23], v1, off offset:896
	global_store_short v[22:23], v1, off offset:1280
	global_store_short v[22:23], v1, off offset:1408
	global_store_short v[22:23], v1, off offset:1792
	global_store_short v[22:23], v1, off offset:1920
	global_store_short v[22:23], v1, off offset:2304
	global_store_short v[22:23], v1, off offset:2432
	global_store_short v[22:23], v1, off offset:2816
	global_store_short v[22:23], v1, off offset:2944
	global_store_short v[22:23], v1, off offset:3328
	global_store_short v[22:23], v1, off offset:3456
	global_store_short v[22:23], v1, off offset:3840
	global_store_short v[22:23], v1, off offset:3968
	global_store_short v[12:13], v1, off offset:256
	global_store_short v[12:13], v1, off offset:384
	global_store_short v[12:13], v1, off offset:768
	global_store_short v[12:13], v1, off offset:896
	global_store_short v[12:13], v1, off offset:1280
	global_store_short v[12:13], v1, off offset:1408
	global_store_short v[12:13], v1, off offset:1792
	global_store_short v[12:13], v1, off offset:1920
	global_store_short v[12:13], v1, off offset:2304
	global_store_short v[12:13], v1, off offset:2432
	global_store_short v[12:13], v1, off offset:2816
	global_store_short v[12:13], v1, off offset:2944
	global_store_short v[12:13], v1, off offset:3328
	global_store_short v[12:13], v1, off offset:3456
	global_store_short v[12:13], v1, off offset:3840
	global_store_short v[12:13], v1, off offset:3968
	s_add_i32 s14, s14, 16
	s_cmpk_lt_u32 s14, 0x70
	s_waitcnt vmcnt(47)
	v_add_f32_e32 v18, v34, v32
	s_waitcnt vmcnt(46)
	v_add_f32_e32 v32, v33, v35
	v_cvt_pk_bf16_f32 v19, v18, s0
	v_cvt_pk_bf16_f32 v34, v32, s0
	v_pk_mul_f32 v[32:33], v[8:9], v[32:33] op_sel_hi:[1,0]
	global_store_short v[22:23], v19, off offset:512
	global_store_short v[22:23], v34, off offset:640
	v_pk_fma_f32 v[34:35], v[2:3], v[18:19], v[32:33] neg_lo:[0,0,1] neg_hi:[0,0,1]
	v_pk_fma_f32 v[18:19], v[2:3], v[18:19], v[32:33] op_sel_hi:[1,0,1]
	s_nop 0
	v_mov_b32_e32 v35, v19
	s_waitcnt vmcnt(46)
	v_pk_add_f32 v[18:19], v[20:21], v[34:35]
	s_nop 0
	v_cvt_pk_bf16_f32 v32, v18, s0
	v_cvt_pk_bf16_f32 v33, v19, s0
	v_pk_mul_f32 v[20:21], v[2:3], v[18:19]
	v_pk_mul_f32 v[18:19], v[2:3], v[18:19] op_sel:[0,1] op_sel_hi:[1,0]
	v_sub_f32_e32 v20, v20, v21
	v_add_f32_e32 v19, v18, v19
	s_waitcnt vmcnt(45)
	v_add_f32_e32 v18, v44, v20
	s_waitcnt vmcnt(44)
	v_add_f32_e32 v20, v45, v19
	global_store_short v[22:23], v32, off offset:1024
	global_store_short v[22:23], v33, off offset:1152
	v_cvt_pk_bf16_f32 v19, v18, s0
	v_cvt_pk_bf16_f32 v32, v20, s0
	v_pk_mul_f32 v[20:21], v[8:9], v[20:21] op_sel_hi:[1,0]
	global_store_short v[22:23], v19, off offset:1536
	global_store_short v[22:23], v32, off offset:1664
	v_pk_fma_f32 v[32:33], v[2:3], v[18:19], v[20:21] neg_lo:[0,0,1] neg_hi:[0,0,1]
	v_pk_fma_f32 v[18:19], v[2:3], v[18:19], v[20:21] op_sel_hi:[1,0,1]
	s_nop 0
	v_mov_b32_e32 v33, v19
	s_waitcnt vmcnt(46)
	v_pk_add_f32 v[18:19], v[26:27], v[32:33]
	s_nop 0
	v_cvt_pk_bf16_f32 v26, v18, s0
	v_cvt_pk_bf16_f32 v27, v19, s0
	v_pk_mul_f32 v[20:21], v[2:3], v[18:19]
	v_pk_mul_f32 v[18:19], v[2:3], v[18:19] op_sel:[0,1] op_sel_hi:[1,0]
	v_sub_f32_e32 v20, v20, v21
	v_add_f32_e32 v19, v18, v19
	s_waitcnt vmcnt(45)
	v_add_f32_e32 v18, v46, v20
	s_waitcnt vmcnt(44)
	v_add_f32_e32 v20, v47, v19
	global_store_short v[22:23], v26, off offset:2048
	global_store_short v[22:23], v27, off offset:2176
	v_cvt_pk_bf16_f32 v19, v18, s0
	v_cvt_pk_bf16_f32 v26, v20, s0
	v_pk_mul_f32 v[20:21], v[8:9], v[20:21] op_sel_hi:[1,0]
	global_store_short v[22:23], v19, off offset:2560
	global_store_short v[22:23], v26, off offset:2688
	v_pk_fma_f32 v[26:27], v[2:3], v[18:19], v[20:21] neg_lo:[0,0,1] neg_hi:[0,0,1]
	v_pk_fma_f32 v[18:19], v[2:3], v[18:19], v[20:21] op_sel_hi:[1,0,1]
	s_nop 0
	v_mov_b32_e32 v27, v19
	s_waitcnt vmcnt(46)
	v_pk_add_f32 v[18:19], v[28:29], v[26:27]
	s_nop 0
	v_cvt_pk_bf16_f32 v26, v18, s0
	v_cvt_pk_bf16_f32 v27, v19, s0
	v_pk_mul_f32 v[20:21], v[2:3], v[18:19]
	v_pk_mul_f32 v[18:19], v[2:3], v[18:19] op_sel:[0,1] op_sel_hi:[1,0]
	v_sub_f32_e32 v20, v20, v21
	v_add_f32_e32 v19, v18, v19
	s_waitcnt vmcnt(45)
	v_add_f32_e32 v18, v48, v20
	s_waitcnt vmcnt(44)
	v_add_f32_e32 v20, v49, v19
	global_store_short v[22:23], v26, off offset:3072
	global_store_short v[22:23], v27, off offset:3200
	v_cvt_pk_bf16_f32 v19, v18, s0
	v_cvt_pk_bf16_f32 v26, v20, s0
	v_pk_mul_f32 v[20:21], v[8:9], v[20:21] op_sel_hi:[1,0]
	global_store_short v[22:23], v19, off offset:3584
	global_store_short v[22:23], v26, off offset:3712
	v_pk_fma_f32 v[22:23], v[2:3], v[18:19], v[20:21] neg_lo:[0,0,1] neg_hi:[0,0,1]
	v_pk_fma_f32 v[18:19], v[2:3], v[18:19], v[20:21] op_sel_hi:[1,0,1]
	s_nop 0
	v_mov_b32_e32 v23, v19
	s_waitcnt vmcnt(46)
	v_pk_add_f32 v[18:19], v[30:31], v[22:23]
	s_nop 0
	v_cvt_pk_bf16_f32 v22, v18, s0
	v_cvt_pk_bf16_f32 v23, v19, s0
	v_pk_mul_f32 v[20:21], v[2:3], v[18:19]
	v_pk_mul_f32 v[18:19], v[2:3], v[18:19] op_sel:[0,1] op_sel_hi:[1,0]
	v_sub_f32_e32 v20, v20, v21
	v_add_f32_e32 v19, v18, v19
	v_add_f32_e32 v18, v36, v20
	v_add_f32_e32 v20, v37, v19
	global_store_short v[12:13], v22, off
	global_store_short v[12:13], v23, off offset:128
	v_cvt_pk_bf16_f32 v19, v18, s0
	v_cvt_pk_bf16_f32 v22, v20, s0
	v_pk_mul_f32 v[20:21], v[8:9], v[20:21] op_sel_hi:[1,0]
	global_store_short v[12:13], v19, off offset:512
	global_store_short v[12:13], v22, off offset:640
	v_pk_fma_f32 v[22:23], v[2:3], v[18:19], v[20:21] neg_lo:[0,0,1] neg_hi:[0,0,1]
	v_pk_fma_f32 v[18:19], v[2:3], v[18:19], v[20:21] op_sel_hi:[1,0,1]
	s_nop 0
	v_mov_b32_e32 v23, v19
	v_pk_add_f32 v[10:11], v[10:11], v[22:23]
	s_nop 0
	v_cvt_pk_bf16_f32 v20, v10, s0
	v_cvt_pk_bf16_f32 v21, v11, s0
	v_pk_mul_f32 v[18:19], v[2:3], v[10:11]
	v_pk_mul_f32 v[10:11], v[2:3], v[10:11] op_sel:[0,1] op_sel_hi:[1,0]
	v_sub_f32_e32 v18, v18, v19
	v_add_f32_e32 v11, v10, v11
	v_add_f32_e32 v10, v38, v18
	v_add_f32_e32 v18, v39, v11
	global_store_short v[12:13], v20, off offset:1024
	global_store_short v[12:13], v21, off offset:1152
	v_cvt_pk_bf16_f32 v11, v10, s0
	v_cvt_pk_bf16_f32 v20, v18, s0
	v_pk_mul_f32 v[18:19], v[8:9], v[18:19] op_sel_hi:[1,0]
	global_store_short v[12:13], v11, off offset:1536
	global_store_short v[12:13], v20, off offset:1664
	v_pk_fma_f32 v[20:21], v[2:3], v[10:11], v[18:19] neg_lo:[0,0,1] neg_hi:[0,0,1]
	v_pk_fma_f32 v[10:11], v[2:3], v[10:11], v[18:19] op_sel_hi:[1,0,1]
	s_nop 0
	v_mov_b32_e32 v21, v11
	v_pk_add_f32 v[10:11], v[14:15], v[20:21]
	s_nop 0
	v_cvt_pk_bf16_f32 v18, v10, s0
	v_cvt_pk_bf16_f32 v19, v11, s0
	v_pk_mul_f32 v[14:15], v[2:3], v[10:11]
	v_pk_mul_f32 v[10:11], v[2:3], v[10:11] op_sel:[0,1] op_sel_hi:[1,0]
	v_sub_f32_e32 v14, v14, v15
	v_add_f32_e32 v11, v10, v11
	v_add_f32_e32 v10, v40, v14
	v_add_f32_e32 v14, v41, v11
	global_store_short v[12:13], v18, off offset:2048
	global_store_short v[12:13], v19, off offset:2176
	v_cvt_pk_bf16_f32 v11, v10, s0
	v_cvt_pk_bf16_f32 v18, v14, s0
	v_pk_mul_f32 v[14:15], v[8:9], v[14:15] op_sel_hi:[1,0]
	global_store_short v[12:13], v11, off offset:2560
	global_store_short v[12:13], v18, off offset:2688
	v_pk_fma_f32 v[18:19], v[2:3], v[10:11], v[14:15] neg_lo:[0,0,1] neg_hi:[0,0,1]
	v_pk_fma_f32 v[10:11], v[2:3], v[10:11], v[14:15] op_sel_hi:[1,0,1]
	s_nop 0
	v_mov_b32_e32 v19, v11
	v_pk_add_f32 v[10:11], v[16:17], v[18:19]
	s_nop 0
	v_cvt_pk_bf16_f32 v16, v10, s0
	v_cvt_pk_bf16_f32 v17, v11, s0
	v_pk_mul_f32 v[14:15], v[2:3], v[10:11]
	v_pk_mul_f32 v[10:11], v[2:3], v[10:11] op_sel:[0,1] op_sel_hi:[1,0]
	v_sub_f32_e32 v14, v14, v15
	v_add_f32_e32 v11, v10, v11
	v_add_f32_e32 v10, v42, v14
	v_add_f32_e32 v14, v43, v11
	global_store_short v[12:13], v16, off offset:3072
	global_store_short v[12:13], v17, off offset:3200
	v_cvt_pk_bf16_f32 v11, v10, s0
	v_cvt_pk_bf16_f32 v16, v14, s0
	v_pk_mul_f32 v[14:15], v[8:9], v[14:15] op_sel_hi:[1,0]
	global_store_short v[12:13], v11, off offset:3584
	global_store_short v[12:13], v16, off offset:3712
	v_pk_fma_f32 v[12:13], v[2:3], v[10:11], v[14:15] neg_lo:[0,0,1] neg_hi:[0,0,1]
	v_pk_fma_f32 v[10:11], v[2:3], v[10:11], v[14:15] op_sel_hi:[1,0,1]
	s_nop 0
	v_mov_b32_e32 v13, v11
	v_pk_add_f32 v[14:15], v[24:25], v[12:13]
	s_cbranch_scc1 .LBB0_1204
